# attention: rope row for the next 16-query strip prefetched one strip ahead, per-strip vmcnt drain replaced by counted waits
# baseline (speedup 1.0000x reference)
; #define LAS __attribute__((address_space(3)))
;     DI bf16_t* fP() const { return (bf16_t*)(ws + WS_P); }
;     DI float* fROPE() const { return (float*)(ws + WS_ROPE); }
; DI void attn_item(const Params& p, const Ctx& c, int l, int S, int tokbase, int qb, int kvh) {
;     ...
;     for (int n = 0; n < 3; ++n) { const int u6 = w + 8 * n, part = u6 / 3, kp = (u6 % 3) * 64 + lane, kpos = kstart + 2 * kp;
;         u32x4 v0 = {0u, 0u, 0u, 0u}, v1 = {0u, 0u, 0u, 0u};
;         const bf16_t* vp = c.fP() + (size_t)(tokbase + kpos) * P1LD + 640 + kvh * 64 + part * 8;
;         if (kpos >= 0 && kpos < S) v0 = *(const u32x4*)vp;
;         if (kpos + 1 >= 0 && kpos + 1 < S) v1 = *(const u32x4*)(vp + P1LD);
;         const unsigned a0[4] = {v0.x, v0.y, v0.z, v0.w}, a1[4] = {v1.x, v1.y, v1.z, v1.w};
; #pragma unroll
;         for (int j = 0; j < 4; ++j) {
;             *(LAS unsigned*)(VTs + (part * 8 + 2 * j) * VP + 2 * kp) = (a0[j] & 0xffffu) | (a1[j] << 16);
;             *(LAS unsigned*)(VTs + (part * 8 + 2 * j + 1) * VP + 2 * kp) = (a0[j] >> 16) | (a1[j] & 0xffff0000u); } }
;     __syncthreads();
;     const int hg = w >> 1, qh = w & 1, head = kvh * 4 + hg;
;     const float sink = p.in[6][l * 8 + head] * 1.4426950408889634f;
;     const bool interior = (kstart >= 0) && (kstart + 384 <= S);
;     float g0[8], g1[8];
; #pragma unroll
;     for (int j = 0; j < 8; ++j) { g0[j] = qg[lg * 8 + j]; g1[j] = qg[32 + lg * 8 + j]; }
;     const bf16_t* qbase = c.fP() + (size_t)(tokbase + qb * 128 + qh * 64 + lr) * P1LD + head * 64 + lg * 8;
;     u32x4 nq0 = *(const u32x4*)qbase, nq1 = *(const u32x4*)(qbase + 32);
; #pragma unroll 1
;     for (int j = 0; j < 4; ++j) {
;         const int qi = qh * 64 + 16 * j + lr, qpos = qb * 128 + qi, kt0 = qh * 4 + j;
;         float f0[8], f1[8]; unpack8(nq0, f0); unpack8(nq1, f1);
;         if (j < 3) { nq0 = *(const u32x4*)(qbase + (size_t)(16 * (j + 1)) * P1LD); nq1 = *(const u32x4*)(qbase + (size_t)(16 * (j + 1)) * P1LD + 32); }
;         float ss = 0.f;
; #pragma unroll
;         for (int i = 0; i < 8; ++i) ss += f0[i] * f0[i] + f1[i] * f1[i];
;         ss += __shfl_xor(ss, 16); ss += __shfl_xor(ss, 32);
;         const float rstd = rsqrtf(ss * (1.f / 64.f) + EPS);
; #pragma unroll
;         for (int i = 0; i < 8; ++i) { f0[i] *= rstd * g0[i]; f1[i] *= rstd * g1[i]; }
;         const float* rr = c.fROPE() + qpos * 16;
.LBB0_315:
	s_or_b64 exec, exec, s[36:37]
	s_mulk_i32 s26, 0x1880
	s_add_i32 s25, s26, 0
	s_waitcnt vmcnt(0)
	v_and_b32_e32 v10, 0xffff, v2
	v_lshl_add_u32 v1, v1, 1, s25
	v_lshrrev_b32_e32 v2, 16, v2
	s_ashr_i32 s25, s33, 7
	s_lshl_b32 s26, s40, 2
	v_lshl_or_b32 v10, v6, 16, v10
	v_and_or_b32 v2, v6, s1, v2
	v_add_u32_e32 v6, 0xd800, v1
	s_add_i32 s26, s25, s26
	v_readlane_b32 s25, v254, 52
	ds_write2_b32 v6, v10, v2 offset1:196
	v_and_b32_e32 v2, 0xffff, v3
	v_lshrrev_b32_e32 v3, 16, v3
	s_add_i32 s36, s26, s25
	v_lshl_or_b32 v2, v7, 16, v2
	v_and_or_b32 v3, v7, s1, v3
	v_add_u32_e32 v6, 0xde00, v1
	s_ashr_i32 s37, s36, 31
	ds_write2_b32 v6, v2, v3 offset0:8 offset1:204
	v_and_b32_e32 v2, 0xffff, v4
	v_lshrrev_b32_e32 v3, 16, v4
	s_lshl_b64 s[36:37], s[36:37], 2
	v_readlane_b32 s38, v253, 61
	v_lshl_or_b32 v2, v8, 16, v2
	v_and_or_b32 v3, v8, s1, v3
	v_add_u32_e32 v4, 0xe400, v1
	v_readlane_b32 s39, v253, 62
	s_add_u32 s36, s38, s36
	ds_write2_b32 v4, v2, v3 offset0:16 offset1:212
	v_and_b32_e32 v2, 0xffff, v5
	v_lshrrev_b32_e32 v3, 16, v5
	s_addc_u32 s37, s39, s37
	v_lshl_or_b32 v2, v9, 16, v2
	v_and_or_b32 v3, v9, s1, v3
	v_add_u32_e32 v1, 0xea00, v1
	s_cmp_gt_i32 s31, s95
	ds_write2_b32 v1, v2, v3 offset0:24 offset1:220
	s_waitcnt lgkmcnt(0)
	s_barrier
	global_load_dword v24, v0, s[36:37]
	s_cselect_b64 s[36:37], -1, 0
	s_bfe_u32 s33, s33, 0x10006
	s_cmp_lt_i32 s24, 1
	v_and_b32_e32 v25, 15, v138
	s_cselect_b64 s[24:25], -1, 0
	s_add_i32 s21, s21, s31
	s_lshl_b32 s31, s33, 6
	v_or_b32_e32 v1, s21, v25
	v_or_b32_e32 v1, s31, v1
	v_mov_b64_e32 v[10:11], s[82:83]
	v_mad_i64_i32 v[10:11], s[38:39], v1, s19, v[10:11]
	s_lshl_b32 s38, s26, 6
	s_ashr_i32 s39, s38, 31
	s_lshl_b64 s[38:39], s[38:39], 1
	v_lshrrev_b32_e32 v22, 4, v18
	v_readlane_b32 s40, v254, 54
	v_lshl_add_u64 v[10:11], v[10:11], 0, s[38:39]
	v_and_b32_e32 v20, 48, v18
	v_mov_b32_e32 v21, v0
	v_lshlrev_b32_e32 v14, 5, v22
	v_readlane_b32 s41, v254, 55
	v_lshl_add_u64 v[10:11], v[10:11], 0, v[20:21]
	s_nop 3
	global_load_dwordx4 v[2:5], v14, s[40:41] offset:16
	global_load_dwordx4 v[6:9], v14, s[40:41]
	global_load_dwordx4 v[30:33], v[10:11], off
	global_load_dwordx4 v[26:29], v[10:11], off offset:64
	s_nop 0
	global_load_dwordx4 v[10:13], v14, s[40:41] offset:144
	s_nop 0
	global_load_dwordx4 v[14:17], v14, s[40:41] offset:128
	v_mbcnt_hi_u32_b32 v21, -1, v206
	v_and_b32_e32 v34, 64, v21
	v_cmp_gt_u32_e64 s[42:43], 16, v18
	v_lshlrev_b32_e32 v18, 3, v22
	v_xor_b32_e32 v23, 16, v21
	v_cmp_eq_u32_e64 s[44:45], 1, v22
	v_lshlrev_b32_e32 v36, 2, v22
	v_add_u32_e32 v22, 64, v34
	v_cmp_lt_i32_e32 vcc, v23, v22
	v_xor_b32_e32 v35, 32, v21
	s_or_b64 s[36:37], s[24:25], s[36:37]
	v_cndmask_b32_e32 v23, v21, v23, vcc
	v_cmp_lt_i32_e32 vcc, v35, v22
	v_lshlrev_b32_e32 v104, 2, v23
	v_mad_i64_i32 v[22:23], s[24:25], v1, s19, 0
	v_readlane_b32 s24, v253, 2
	v_readlane_b32 s25, v253, 3
	s_add_u32 s24, s24, s38
	v_mov_b32_e32 v19, v0
	v_cndmask_b32_e32 v21, v21, v35, vcc
	s_addc_u32 s25, s25, s39
	v_readlane_b32 s21, v253, 44
	v_lshlrev_b32_e32 v105, 2, v21
	v_or_b32_e32 v21, 1, v36
	v_lshl_add_u64 v[98:99], s[24:25], 0, v[18:19]
	s_add_u32 s24, s21, s38
	v_readlane_b32 s21, v253, 45
	v_cmp_ge_u32_e64 s[48:49], v21, v25
	v_cmp_lt_u32_e64 s[62:63], v21, v25
	v_mul_u32_u24_e32 v21, 0x310, v25
	s_addc_u32 s25, s21, s39
	s_lshl_b32 s21, s33, 7
	s_lshl_b32 s2, s2, 7
	v_add3_u32 v107, v21, s21, v18
	s_mulk_i32 s33, 0x2400
	v_mul_u32_u24_e32 v18, 0x90, v25
	s_or_b32 s2, s2, s31
	v_readlane_b32 s21, v255, 13
	v_add3_u32 v108, s33, v18, v20
	s_mul_i32 s20, s21, s20
	v_or_b32_e32 v18, s2, v36
	v_subrev_u32_e32 v109, s20, v18
	v_or_b32_e32 v18, s2, v25
	v_or_b32_e32 v34, 3, v36
	v_and_or_b32 v22, v138, 48, v22
	v_subrev_u32_e32 v18, s20, v18
	v_cmp_ge_u32_e64 s[46:47], v36, v25
	v_cmp_ge_u32_e64 s[52:53], v34, v25
	v_cmp_le_u32_e64 s[54:55], v36, v25
	v_cmp_lt_u32_e64 s[56:57], v36, v25
	v_cmp_le_u32_e64 s[60:61], v34, v25
	v_cmp_lt_u32_e64 s[66:67], v34, v25
	v_cmp_gt_u32_e64 s[68:69], v36, v25
	s_waitcnt vmcnt(6)
	v_mul_f32_e32 v106, 0x3fb8aa3b, v24
	v_or_b32_e32 v24, 2, v36
	v_cmp_ge_u32_e64 s[50:51], v24, v25
	v_cmp_le_u32_e64 s[58:59], v24, v25
	v_cmp_lt_u32_e64 s[64:65], v24, v25
	v_cmp_gt_u32_e64 s[70:71], v24, v25
	v_cmp_gt_u32_e64 s[72:73], v34, v25
	v_lshl_add_u64 v[100:101], s[24:25], 0, v[22:23]
	v_lshlrev_b32_e32 v102, 4, v18
	s_mov_b32 s40, 0
	s_sub_i32 s41, s2, s20
	s_waitcnt vmcnt(3)
	v_mov_b64_e32 v[22:23], v[30:31]
	s_waitcnt vmcnt(2)
	v_mov_b64_e32 v[18:19], v[26:27]
	v_mov_b64_e32 v[20:21], v[28:29]
	v_mov_b64_e32 v[24:25], v[32:33]
	v_readlane_b32 s24, v254, 25
	v_readlane_b32 s25, v254, 26
	v_ashrrev_i32_e32 v243, 31, v102
	v_mov_b32_e32 v242, v102
	s_nop 1
	v_lshl_add_u64 v[242:243], v[242:243], 2, s[24:25]
	global_load_dwordx4 v[238:241], v[242:243], off offset:48
	global_load_dwordx4 v[234:237], v[242:243], off offset:32
	global_load_dwordx4 v[230:233], v[242:243], off offset:16
	global_load_dwordx4 v[226:229], v[242:243], off
	s_waitcnt vmcnt(0)
	s_branch .LBB0_317
; DI u32x4 pack8(const float* f) { u32x4 w; w.x = pk2(f[0], f[1]); w.y = pk2(f[2], f[3]); w.z = pk2(f[4], f[5]); w.w = pk2(f[6], f[7]); return w; }
; DI void attn_item(const Params& p, const Ctx& c, int l, int S, int tokbase, int qb, int kvh) {
;     ...
;         mx = fmaxf(mx, __shfl_xor(mx, 16)); mx = fmaxf(mx, __shfl_xor(mx, 32));
;         float sum = 0.f;
; #pragma unroll
;         for (int t = 0; t < 17; ++t)
; #pragma unroll
;             for (int r = 0; r < 4; ++r) { const float pv = __builtin_amdgcn_exp2f(s[t][r] - mx); s[t][r] = pv; sum += pv; }
;         sum += __shfl_xor(sum, 16); sum += __shfl_xor(sum, 32);
;         sum += __builtin_amdgcn_exp2f(sink - mx);
;         f32x4 o[4];
; #pragma unroll
;         for (int dt = 0; dt < 4; ++dt) o[dt] = (f32x4){0.f, 0.f, 0.f, 0.f};
; #pragma unroll
;         for (int u = 0; u < 9; ++u) {
;             float g[8];
; #pragma unroll
;             for (int r = 0; r < 4; ++r) { g[r] = s[2 * u][r]; g[4 + r] = (2 * u + 1 < 17) ? s[(2 * u + 1 < 17) ? 2 * u + 1 : 0][r] : 0.f; }
;             const bf16x8 bfr = __builtin_bit_cast(bf16x8, pack8(g));
.LBB0_316:
	ds_bpermute_b32 v216, v104, v188
	v_max_f32_e32 v217, v188, v188
	v_add_u32_e32 v108, 0x900, v108
	v_add_u32_e32 v102, 0x100, v102
	s_waitcnt lgkmcnt(0)
	v_max_f32_e32 v216, v216, v216
	v_max_f32_e32 v216, v217, v216
	ds_bpermute_b32 v217, v105, v216
	s_waitcnt lgkmcnt(0)
	v_max_f32_e32 v217, v217, v217
	v_max_f32_e32 v218, v216, v217
	s_nop 0
	v_pk_add_f32 v[26:27], v[26:27], v[218:219] op_sel_hi:[1,0] neg_lo:[0,1] neg_hi:[0,1]
	v_pk_add_f32 v[28:29], v[28:29], v[218:219] op_sel_hi:[1,0] neg_lo:[0,1] neg_hi:[0,1]
	v_pk_add_f32 v[30:31], v[30:31], v[218:219] op_sel_hi:[1,0] neg_lo:[0,1] neg_hi:[0,1]
	v_pk_add_f32 v[32:33], v[32:33], v[218:219] op_sel_hi:[1,0] neg_lo:[0,1] neg_hi:[0,1]
	v_pk_add_f32 v[34:35], v[34:35], v[218:219] op_sel_hi:[1,0] neg_lo:[0,1] neg_hi:[0,1]
	v_pk_add_f32 v[36:37], v[36:37], v[218:219] op_sel_hi:[1,0] neg_lo:[0,1] neg_hi:[0,1]
	v_pk_add_f32 v[38:39], v[38:39], v[218:219] op_sel_hi:[1,0] neg_lo:[0,1] neg_hi:[0,1]
	v_pk_add_f32 v[40:41], v[40:41], v[218:219] op_sel_hi:[1,0] neg_lo:[0,1] neg_hi:[0,1]
	v_pk_add_f32 v[42:43], v[42:43], v[218:219] op_sel_hi:[1,0] neg_lo:[0,1] neg_hi:[0,1]
	v_pk_add_f32 v[44:45], v[44:45], v[218:219] op_sel_hi:[1,0] neg_lo:[0,1] neg_hi:[0,1]
	v_pk_add_f32 v[46:47], v[46:47], v[218:219] op_sel_hi:[1,0] neg_lo:[0,1] neg_hi:[0,1]
	v_pk_add_f32 v[48:49], v[48:49], v[218:219] op_sel_hi:[1,0] neg_lo:[0,1] neg_hi:[0,1]
	v_pk_add_f32 v[50:51], v[50:51], v[218:219] op_sel_hi:[1,0] neg_lo:[0,1] neg_hi:[0,1]
	v_pk_add_f32 v[52:53], v[52:53], v[218:219] op_sel_hi:[1,0] neg_lo:[0,1] neg_hi:[0,1]
	v_pk_add_f32 v[54:55], v[54:55], v[218:219] op_sel_hi:[1,0] neg_lo:[0,1] neg_hi:[0,1]
	v_pk_add_f32 v[56:57], v[56:57], v[218:219] op_sel_hi:[1,0] neg_lo:[0,1] neg_hi:[0,1]
	v_pk_add_f32 v[58:59], v[58:59], v[218:219] op_sel_hi:[1,0] neg_lo:[0,1] neg_hi:[0,1]
	v_pk_add_f32 v[60:61], v[60:61], v[218:219] op_sel_hi:[1,0] neg_lo:[0,1] neg_hi:[0,1]
	v_pk_add_f32 v[62:63], v[62:63], v[218:219] op_sel_hi:[1,0] neg_lo:[0,1] neg_hi:[0,1]
	v_pk_add_f32 v[64:65], v[64:65], v[218:219] op_sel_hi:[1,0] neg_lo:[0,1] neg_hi:[0,1]
	v_pk_add_f32 v[66:67], v[66:67], v[218:219] op_sel_hi:[1,0] neg_lo:[0,1] neg_hi:[0,1]
	v_pk_add_f32 v[68:69], v[68:69], v[218:219] op_sel_hi:[1,0] neg_lo:[0,1] neg_hi:[0,1]
	v_pk_add_f32 v[70:71], v[70:71], v[218:219] op_sel_hi:[1,0] neg_lo:[0,1] neg_hi:[0,1]
	v_pk_add_f32 v[72:73], v[72:73], v[218:219] op_sel_hi:[1,0] neg_lo:[0,1] neg_hi:[0,1]
	v_pk_add_f32 v[74:75], v[74:75], v[218:219] op_sel_hi:[1,0] neg_lo:[0,1] neg_hi:[0,1]
	v_pk_add_f32 v[76:77], v[76:77], v[218:219] op_sel_hi:[1,0] neg_lo:[0,1] neg_hi:[0,1]
	v_pk_add_f32 v[78:79], v[78:79], v[218:219] op_sel_hi:[1,0] neg_lo:[0,1] neg_hi:[0,1]
	v_pk_add_f32 v[80:81], v[80:81], v[218:219] op_sel_hi:[1,0] neg_lo:[0,1] neg_hi:[0,1]
	v_pk_add_f32 v[82:83], v[82:83], v[218:219] op_sel_hi:[1,0] neg_lo:[0,1] neg_hi:[0,1]
	v_pk_add_f32 v[84:85], v[84:85], v[218:219] op_sel_hi:[1,0] neg_lo:[0,1] neg_hi:[0,1]
	v_pk_add_f32 v[86:87], v[86:87], v[218:219] op_sel_hi:[1,0] neg_lo:[0,1] neg_hi:[0,1]
	v_pk_add_f32 v[88:89], v[88:89], v[218:219] op_sel_hi:[1,0] neg_lo:[0,1] neg_hi:[0,1]
	v_pk_add_f32 v[90:91], v[90:91], v[218:219] op_sel_hi:[1,0] neg_lo:[0,1] neg_hi:[0,1]
	v_pk_add_f32 v[92:93], v[92:93], v[218:219] op_sel_hi:[1,0] neg_lo:[0,1] neg_hi:[0,1]
	v_exp_f32_e32 v26, v26
	v_exp_f32_e32 v27, v27
	v_exp_f32_e32 v28, v28
	v_exp_f32_e32 v29, v29
	v_exp_f32_e32 v30, v30
	v_exp_f32_e32 v31, v31
	v_exp_f32_e32 v32, v32
	v_exp_f32_e32 v33, v33
	v_exp_f32_e32 v34, v34
	v_exp_f32_e32 v35, v35
	v_exp_f32_e32 v36, v36
	v_exp_f32_e32 v37, v37
	v_exp_f32_e32 v38, v38
	v_exp_f32_e32 v39, v39
	v_exp_f32_e32 v40, v40
	v_exp_f32_e32 v41, v41
	v_exp_f32_e32 v42, v42
	v_exp_f32_e32 v43, v43
	v_exp_f32_e32 v44, v44
	v_exp_f32_e32 v45, v45
	v_exp_f32_e32 v46, v46
	v_exp_f32_e32 v47, v47
	v_exp_f32_e32 v48, v48
	v_exp_f32_e32 v49, v49
	v_exp_f32_e32 v50, v50
	v_exp_f32_e32 v51, v51
	v_exp_f32_e32 v52, v52
	v_exp_f32_e32 v53, v53
	v_exp_f32_e32 v54, v54
	v_exp_f32_e32 v55, v55
	v_exp_f32_e32 v56, v56
	v_exp_f32_e32 v57, v57
	v_exp_f32_e32 v58, v58
	v_exp_f32_e32 v59, v59
	v_exp_f32_e32 v60, v60
	v_exp_f32_e32 v61, v61
	v_exp_f32_e32 v62, v62
	v_exp_f32_e32 v63, v63
	v_exp_f32_e32 v64, v64
	v_exp_f32_e32 v65, v65
	v_exp_f32_e32 v66, v66
	v_exp_f32_e32 v67, v67
	v_exp_f32_e32 v68, v68
	v_exp_f32_e32 v69, v69
	v_exp_f32_e32 v70, v70
	v_exp_f32_e32 v71, v71
	v_exp_f32_e32 v72, v72
	v_exp_f32_e32 v73, v73
	v_exp_f32_e32 v74, v74
	v_exp_f32_e32 v75, v75
	v_exp_f32_e32 v76, v76
	v_exp_f32_e32 v77, v77
	v_exp_f32_e32 v78, v78
	v_exp_f32_e32 v79, v79
	v_exp_f32_e32 v80, v80
	v_exp_f32_e32 v81, v81
	v_exp_f32_e32 v82, v82
	v_exp_f32_e32 v83, v83
	v_exp_f32_e32 v84, v84
	v_exp_f32_e32 v85, v85
	v_exp_f32_e32 v86, v86
	v_exp_f32_e32 v87, v87
	v_exp_f32_e32 v88, v88
	v_exp_f32_e32 v89, v89
	v_exp_f32_e32 v90, v90
	v_exp_f32_e32 v91, v91
	v_exp_f32_e32 v92, v92
	v_exp_f32_e32 v93, v93
	v_pk_add_f32 v[220:221], v[26:27], v[28:29]
	v_pk_add_f32 v[220:221], v[220:221], v[30:31]
	v_pk_add_f32 v[220:221], v[220:221], v[32:33]
	v_pk_add_f32 v[220:221], v[220:221], v[34:35]
	v_pk_add_f32 v[220:221], v[220:221], v[36:37]
	v_pk_add_f32 v[220:221], v[220:221], v[38:39]
	v_pk_add_f32 v[220:221], v[220:221], v[40:41]
	v_pk_add_f32 v[220:221], v[220:221], v[42:43]
	v_pk_add_f32 v[220:221], v[220:221], v[44:45]
	v_pk_add_f32 v[220:221], v[220:221], v[46:47]
	v_pk_add_f32 v[220:221], v[220:221], v[48:49]
	v_pk_add_f32 v[220:221], v[220:221], v[50:51]
	v_pk_add_f32 v[220:221], v[220:221], v[52:53]
	v_pk_add_f32 v[220:221], v[220:221], v[54:55]
	v_pk_add_f32 v[220:221], v[220:221], v[56:57]
	v_pk_add_f32 v[220:221], v[220:221], v[58:59]
	v_pk_add_f32 v[220:221], v[220:221], v[60:61]
	v_pk_add_f32 v[220:221], v[220:221], v[62:63]
	v_pk_add_f32 v[220:221], v[220:221], v[64:65]
	v_pk_add_f32 v[220:221], v[220:221], v[66:67]
	v_pk_add_f32 v[220:221], v[220:221], v[68:69]
	v_pk_add_f32 v[220:221], v[220:221], v[70:71]
	v_pk_add_f32 v[220:221], v[220:221], v[72:73]
	v_pk_add_f32 v[220:221], v[220:221], v[74:75]
	v_pk_add_f32 v[220:221], v[220:221], v[76:77]
	v_pk_add_f32 v[220:221], v[220:221], v[78:79]
	v_pk_add_f32 v[220:221], v[220:221], v[80:81]
	v_pk_add_f32 v[220:221], v[220:221], v[82:83]
	v_pk_add_f32 v[220:221], v[220:221], v[84:85]
	v_pk_add_f32 v[220:221], v[220:221], v[86:87]
	v_pk_add_f32 v[220:221], v[220:221], v[88:89]
	v_pk_add_f32 v[220:221], v[220:221], v[90:91]
	v_pk_add_f32 v[220:221], v[220:221], v[92:93]
	v_add_f32_e32 v224, v220, v221
	ds_bpermute_b32 v225, v104, v224
	v_sub_f32_e32 v222, v106, v218
	v_cvt_pk_bf16_f32 v130, v26, v27
	v_cvt_pk_bf16_f32 v131, v28, v29
	v_cvt_pk_bf16_f32 v132, v30, v31
	v_cvt_pk_bf16_f32 v133, v32, v33
	v_cvt_pk_bf16_f32 v134, v34, v35
	v_cvt_pk_bf16_f32 v135, v36, v37
	v_cvt_pk_bf16_f32 v136, v38, v39
	v_cvt_pk_bf16_f32 v137, v40, v41
	v_cvt_pk_bf16_f32 v138, v42, v43
	v_cvt_pk_bf16_f32 v139, v44, v45
	v_cvt_pk_bf16_f32 v140, v46, v47
	v_cvt_pk_bf16_f32 v141, v48, v49
	s_waitcnt lgkmcnt(0)
; #define LAS __attribute__((address_space(3)))
; DI u32x4 pack8(const float* f) { u32x4 w; w.x = pk2(f[0], f[1]); w.y = pk2(f[2], f[3]); w.z = pk2(f[4], f[5]); w.w = pk2(f[6], f[7]); return w; }
; DI void attn_item(const Params& p, const Ctx& c, int l, int S, int tokbase, int qb, int kvh) {
;     ...
;         sum += __shfl_xor(sum, 16); sum += __shfl_xor(sum, 32);
;         sum += __builtin_amdgcn_exp2f(sink - mx);
;         f32x4 o[4];
; #pragma unroll
;         for (int dt = 0; dt < 4; ++dt) o[dt] = (f32x4){0.f, 0.f, 0.f, 0.f};
; #pragma unroll
;         for (int u = 0; u < 9; ++u) {
;             float g[8];
; #pragma unroll
;             for (int r = 0; r < 4; ++r) { g[r] = s[2 * u][r]; g[4 + r] = (2 * u + 1 < 17) ? s[(2 * u + 1 < 17) ? 2 * u + 1 : 0][r] : 0.f; }
;             const bf16x8 bfr = __builtin_bit_cast(bf16x8, pack8(g));
; #pragma unroll
;             for (int dt = 0; dt < 4; ++dt) {
;                 const LAS bf16_t* vr = VTs + (dt * 16 + lr) * VP + (kt0 + 2 * u) * 16 + lg * 4;
;                 const s16x4 lo = *(const LAS s16x4*)vr;
;                 s16x4 hi = (s16x4){0, 0, 0, 0};
;                 if (2 * u + 1 < 17) hi = *(const LAS s16x4*)(vr + 16);
;                 o[dt] = __builtin_amdgcn_mfma_f32_16x16x32_bf16(__builtin_shufflevector(lo, hi, 0, 1, 2, 3, 4, 5, 6, 7), bfr, o[dt], 0, 0, 0); }
	v_add_f32_e32 v225, v224, v225
	v_exp_f32_e32 v224, v222
	ds_bpermute_b32 v122, v105, v225
	v_cvt_pk_bf16_f32 v142, v50, v51
	v_cvt_pk_bf16_f32 v143, v52, v53
	v_cvt_pk_bf16_f32 v144, v54, v55
	v_cvt_pk_bf16_f32 v145, v56, v57
	v_cvt_pk_bf16_f32 v146, v58, v59
	v_cvt_pk_bf16_f32 v147, v60, v61
	v_cvt_pk_bf16_f32 v148, v62, v63
	v_cvt_pk_bf16_f32 v149, v64, v65
	v_cvt_pk_bf16_f32 v150, v66, v67
	v_cvt_pk_bf16_f32 v151, v68, v69
	v_cvt_pk_bf16_f32 v152, v70, v71
	v_cvt_pk_bf16_f32 v153, v72, v73
	v_cvt_pk_bf16_f32 v154, v74, v75
	v_cvt_pk_bf16_f32 v155, v76, v77
	v_cvt_pk_bf16_f32 v156, v78, v79
	v_cvt_pk_bf16_f32 v157, v80, v81
	v_cvt_pk_bf16_f32 v158, v82, v83
	v_cvt_pk_bf16_f32 v159, v84, v85
	v_cvt_pk_bf16_f32 v160, v86, v87
	v_cvt_pk_bf16_f32 v161, v88, v89
	v_cvt_pk_bf16_f32 v162, v90, v91
	v_cvt_pk_bf16_f32 v163, v92, v93
	v_mov_b32_e32 v164, 0
	v_mov_b32_e32 v165, 0
	v_add_u32_e32 v123, 0xd800, v107
	v_add_u32_e32 v124, 0x10900, v107
	v_add_u32_e32 v125, 0x13a00, v107
	v_add_u32_e32 v126, 0x16b00, v107
	v_add_u32_e32 v107, 32, v107
	ds_read2_b64 v[48:51], v123 offset1:4
	ds_read2_b64 v[52:55], v124 offset1:4
	ds_read2_b64 v[56:59], v125 offset1:4
	ds_read2_b64 v[60:63], v126 offset1:4
	ds_read2_b64 v[64:67], v123 offset0:8 offset1:12
	ds_read2_b64 v[68:71], v124 offset0:8 offset1:12
	ds_read2_b64 v[72:75], v125 offset0:8 offset1:12
	ds_read2_b64 v[76:79], v126 offset0:8 offset1:12
	ds_read2_b64 v[80:83], v123 offset0:16 offset1:20
	ds_read2_b64 v[84:87], v124 offset0:16 offset1:20
	ds_read2_b64 v[88:91], v125 offset0:16 offset1:20
	ds_read2_b64 v[92:95], v126 offset0:16 offset1:20
	s_waitcnt lgkmcnt(8)
	v_add_f32_e32 v225, v225, v122
	v_mfma_f32_16x16x32_bf16 v[42:45], v[48:51], v[130:133], 0
	v_mfma_f32_16x16x32_bf16 v[38:41], v[52:55], v[130:133], 0
	v_mfma_f32_16x16x32_bf16 v[34:37], v[56:59], v[130:133], 0
	v_mfma_f32_16x16x32_bf16 v[26:29], v[60:63], v[130:133], 0
	ds_read2_b64 v[48:51], v123 offset0:24 offset1:28
	ds_read2_b64 v[52:55], v124 offset0:24 offset1:28
	ds_read2_b64 v[56:59], v125 offset0:24 offset1:28
	ds_read2_b64 v[60:63], v126 offset0:24 offset1:28
	s_waitcnt lgkmcnt(8)
	v_mfma_f32_16x16x32_bf16 v[42:45], v[64:67], v[134:137], v[42:45]
	v_mfma_f32_16x16x32_bf16 v[38:41], v[68:71], v[134:137], v[38:41]
	v_mfma_f32_16x16x32_bf16 v[34:37], v[72:75], v[134:137], v[34:37]
	v_mfma_f32_16x16x32_bf16 v[26:29], v[76:79], v[134:137], v[26:29]
	ds_read2_b64 v[64:67], v123 offset0:32 offset1:36
	ds_read2_b64 v[68:71], v124 offset0:32 offset1:36
	ds_read2_b64 v[72:75], v125 offset0:32 offset1:36
	ds_read2_b64 v[76:79], v126 offset0:32 offset1:36
	s_waitcnt lgkmcnt(8)
	v_mfma_f32_16x16x32_bf16 v[42:45], v[80:83], v[138:141], v[42:45]
	v_mfma_f32_16x16x32_bf16 v[38:41], v[84:87], v[138:141], v[38:41]
	v_mfma_f32_16x16x32_bf16 v[34:37], v[88:91], v[138:141], v[34:37]
	v_mfma_f32_16x16x32_bf16 v[26:29], v[92:95], v[138:141], v[26:29]
	ds_read2_b64 v[80:83], v123 offset0:40 offset1:44
	ds_read2_b64 v[84:87], v124 offset0:40 offset1:44
	ds_read2_b64 v[88:91], v125 offset0:40 offset1:44
	ds_read2_b64 v[92:95], v126 offset0:40 offset1:44
	s_waitcnt lgkmcnt(8)
	v_mfma_f32_16x16x32_bf16 v[42:45], v[48:51], v[142:145], v[42:45]
	v_mfma_f32_16x16x32_bf16 v[38:41], v[52:55], v[142:145], v[38:41]
	v_mfma_f32_16x16x32_bf16 v[34:37], v[56:59], v[142:145], v[34:37]
	v_mfma_f32_16x16x32_bf16 v[26:29], v[60:63], v[142:145], v[26:29]
	ds_read2_b64 v[48:51], v123 offset0:48 offset1:52
	ds_read2_b64 v[52:55], v124 offset0:48 offset1:52
	ds_read2_b64 v[56:59], v125 offset0:48 offset1:52
	ds_read2_b64 v[60:63], v126 offset0:48 offset1:52
	s_waitcnt lgkmcnt(8)
	v_mfma_f32_16x16x32_bf16 v[42:45], v[64:67], v[146:149], v[42:45]
	v_mfma_f32_16x16x32_bf16 v[38:41], v[68:71], v[146:149], v[38:41]
	v_mfma_f32_16x16x32_bf16 v[34:37], v[72:75], v[146:149], v[34:37]
	v_mfma_f32_16x16x32_bf16 v[26:29], v[76:79], v[146:149], v[26:29]
	ds_read2_b64 v[64:67], v123 offset0:56 offset1:60
	ds_read2_b64 v[68:71], v124 offset0:56 offset1:60
	ds_read2_b64 v[72:75], v125 offset0:56 offset1:60
	ds_read2_b64 v[76:79], v126 offset0:56 offset1:60
	s_waitcnt lgkmcnt(8)
	v_mfma_f32_16x16x32_bf16 v[42:45], v[80:83], v[150:153], v[42:45]
	v_mfma_f32_16x16x32_bf16 v[38:41], v[84:87], v[150:153], v[38:41]
	v_mfma_f32_16x16x32_bf16 v[34:37], v[88:91], v[150:153], v[34:37]
	v_mfma_f32_16x16x32_bf16 v[26:29], v[92:95], v[150:153], v[26:29]
	ds_read_b64 v[80:81], v123 offset:512
	ds_read_b64 v[84:85], v124 offset:512
	ds_read_b64 v[88:89], v125 offset:512
	ds_read_b64 v[92:93], v126 offset:512
	v_mov_b64_e32 v[82:83], 0
	v_mov_b64_e32 v[86:87], 0
	v_mov_b64_e32 v[90:91], 0
	v_mov_b64_e32 v[94:95], 0
	s_waitcnt lgkmcnt(8)
	v_mfma_f32_16x16x32_bf16 v[42:45], v[48:51], v[154:157], v[42:45]
	v_mfma_f32_16x16x32_bf16 v[38:41], v[52:55], v[154:157], v[38:41]
	v_mfma_f32_16x16x32_bf16 v[34:37], v[56:59], v[154:157], v[34:37]
	v_mfma_f32_16x16x32_bf16 v[26:29], v[60:63], v[154:157], v[26:29]
	s_waitcnt lgkmcnt(4)
	v_mfma_f32_16x16x32_bf16 v[42:45], v[64:67], v[158:161], v[42:45]
	v_mfma_f32_16x16x32_bf16 v[38:41], v[68:71], v[158:161], v[38:41]
	v_mfma_f32_16x16x32_bf16 v[34:37], v[72:75], v[158:161], v[34:37]
	v_mfma_f32_16x16x32_bf16 v[26:29], v[76:79], v[158:161], v[26:29]
	s_waitcnt lgkmcnt(0)
; DI unsigned pk2(float lo, float hi) { const f2_t v = {lo, hi}; const bf2_t r = __builtin_convertvector(v, bf2_t); return __builtin_bit_cast(unsigned, r); }
;     DI bf16_t* fOUTS() const { return (bf16_t*)(ws + WS_OUTS); }
;     DI float* fROPE() const { return (float*)(ws + WS_ROPE); }
; DI void attn_item(const Params& p, const Ctx& c, int l, int S, int tokbase, int qb, int kvh) {
;     ...
;     for (int j = 0; j < 4; ++j) {
;         const int qi = qh * 64 + 16 * j + lr, qpos = qb * 128 + qi, kt0 = qh * 4 + j;
;         float f0[8], f1[8]; unpack8(nq0, f0); unpack8(nq1, f1);
;         if (j < 3) { nq0 = *(const u32x4*)(qbase + (size_t)(16 * (j + 1)) * P1LD); nq1 = *(const u32x4*)(qbase + (size_t)(16 * (j + 1)) * P1LD + 32); }
;         float ss = 0.f;
; #pragma unroll
;         for (int i = 0; i < 8; ++i) ss += f0[i] * f0[i] + f1[i] * f1[i];
;         ss += __shfl_xor(ss, 16); ss += __shfl_xor(ss, 32);
;         const float rstd = rsqrtf(ss * (1.f / 64.f) + EPS);
; #pragma unroll
;         for (int i = 0; i < 8; ++i) { f0[i] *= rstd * g0[i]; f1[i] *= rstd * g1[i]; }
;         const float* rr = c.fROPE() + qpos * 16;
; #pragma unroll
;         for (int i = 0; i < 8; ++i) { const float other = __shfl_xor(f0[i], 16), cs = rr[i], sn = rr[8 + i];
;             if (lg == 0) f0[i] = f0[i] * cs - other * sn; else if (lg == 1) f0[i] = f0[i] * cs + other * sn; }
;     ...
;         const float inv = 1.f / sum;
;         bf16_t* op = c.fOUTS() + (size_t)(tokbase + qpos) * OLD + head * 64 + lg * 4;
; #pragma unroll
;         for (int dt = 0; dt < 4; ++dt) { u32x2 ov; ov.x = pk2(o[dt][0] * inv, o[dt][1] * inv); ov.y = pk2(o[dt][2] * inv, o[dt][3] * inv); *(u32x2*)(op + dt * 16) = ov; }
	v_mfma_f32_16x16x32_bf16 v[42:45], v[80:83], v[162:165], v[42:45]
	v_mfma_f32_16x16x32_bf16 v[38:41], v[84:87], v[162:165], v[38:41]
	v_mfma_f32_16x16x32_bf16 v[34:37], v[88:91], v[162:165], v[34:37]
	v_mfma_f32_16x16x32_bf16 v[26:29], v[92:95], v[162:165], v[26:29]
	v_add_f32_e32 v30, v224, v225
	v_div_scale_f32 v31, s[20:21], v30, v30, 1.0
	v_rcp_f32_e32 v32, v31
	s_nop 0
	v_fma_f32 v33, -v31, v32, 1.0
	v_fmac_f32_e32 v32, v33, v32
	v_div_scale_f32 v33, vcc, 1.0, v30, 1.0
	v_mul_f32_e32 v46, v33, v32
	v_fma_f32 v47, -v31, v46, v33
	v_fmac_f32_e32 v46, v47, v32
	v_fma_f32 v31, -v31, v46, v33
	v_div_fmas_f32 v31, v31, v32, v46
	v_div_fixup_f32 v30, v31, v30, 1.0
	v_add_u32_e32 v31, s40, v1
	v_pk_mul_f32 v[42:43], v[30:31], v[42:43] op_sel_hi:[0,1]
	v_pk_mul_f32 v[44:45], v[30:31], v[44:45] op_sel_hi:[0,1]
	v_pk_mul_f32 v[38:39], v[30:31], v[38:39] op_sel_hi:[0,1]
	v_pk_mul_f32 v[40:41], v[30:31], v[40:41] op_sel_hi:[0,1]
	v_pk_mul_f32 v[34:35], v[30:31], v[34:35] op_sel_hi:[0,1]
	v_pk_mul_f32 v[36:37], v[30:31], v[36:37] op_sel_hi:[0,1]
	v_pk_mul_f32 v[26:27], v[30:31], v[26:27] op_sel_hi:[0,1]
	v_pk_mul_f32 v[28:29], v[30:31], v[28:29] op_sel_hi:[0,1]
	v_mad_i64_i32 v[32:33], s[20:21], v31, s22, v[98:99]
	v_cvt_pk_bf16_f32 v42, v42, v43
	v_cvt_pk_bf16_f32 v43, v44, v45
	v_cvt_pk_bf16_f32 v38, v38, v39
	v_cvt_pk_bf16_f32 v39, v40, v41
	v_cvt_pk_bf16_f32 v34, v34, v35
	v_cvt_pk_bf16_f32 v35, v36, v37
	v_cvt_pk_bf16_f32 v26, v26, v27
	v_cvt_pk_bf16_f32 v27, v28, v29
	global_store_dwordx2 v[32:33], v[42:43], off
	global_store_dwordx2 v[32:33], v[38:39], off offset:32
	global_store_dwordx2 v[32:33], v[34:35], off offset:64
	global_store_dwordx2 v[32:33], v[26:27], off offset:96
	s_mov_b64 s[20:21], 0x18000
	s_add_i32 s40, s40, 16
	s_waitcnt vmcnt(8)
	v_mov_b64_e32 v[32:33], v[24:25]
	v_mov_b64_e32 v[28:29], v[20:21]
	v_lshl_add_u64 v[100:101], v[100:101], 0, s[20:21]
	s_cmp_lg_u32 s40, 64
	v_mov_b64_e32 v[30:31], v[22:23]
	v_mov_b64_e32 v[26:27], v[18:19]
	s_cbranch_scc0 .LBB0_323
.LBB0_317:
	s_waitcnt vmcnt(4)
	s_cmp_eq_u32 s40, 48
	s_cbranch_scc1 .LBB0_319
	global_load_dwordx4 v[22:25], v[100:101], off
	global_load_dwordx4 v[18:21], v[100:101], off offset:64
.LBB0_319:
	v_lshlrev_b32_e32 v56, 16, v26
	v_and_b32_e32 v57, 0xffff0000, v26
	v_lshlrev_b32_e32 v34, 16, v30
	v_and_b32_e32 v35, 0xffff0000, v30
	v_lshlrev_b32_e32 v52, 16, v27
	v_and_b32_e32 v53, 0xffff0000, v27
	v_pk_mul_f32 v[26:27], v[56:57], v[56:57]
	v_lshlrev_b32_e32 v54, 16, v31
	v_and_b32_e32 v55, 0xffff0000, v31
	v_lshlrev_b32_e32 v48, 16, v28
	v_and_b32_e32 v49, 0xffff0000, v28
	v_lshlrev_b32_e32 v42, 16, v29
	v_and_b32_e32 v43, 0xffff0000, v29
	v_pk_fma_f32 v[26:27], v[34:35], v[34:35], v[26:27]
	v_pk_mul_f32 v[28:29], v[52:53], v[52:53]
	v_add_f32_e32 v26, v26, v27
	v_pk_fma_f32 v[28:29], v[54:55], v[54:55], v[28:29]
	v_lshlrev_b32_e32 v50, 16, v32
	v_and_b32_e32 v51, 0xffff0000, v32
	v_pk_mul_f32 v[30:31], v[48:49], v[48:49]
	v_add_f32_e32 v26, v28, v26
	v_pk_fma_f32 v[30:31], v[50:51], v[50:51], v[30:31]
	v_add_f32_e32 v26, v29, v26
	v_lshlrev_b32_e32 v44, 16, v33
	v_and_b32_e32 v45, 0xffff0000, v33
	v_pk_mul_f32 v[32:33], v[42:43], v[42:43]
	v_add_f32_e32 v26, v30, v26
	v_pk_fma_f32 v[32:33], v[44:45], v[44:45], v[32:33]
	v_add_f32_e32 v26, v31, v26
	v_add_f32_e32 v26, v32, v26
	v_add_f32_e32 v26, v33, v26
	ds_bpermute_b32 v27, v104, v26
	v_readlane_b32 s20, v254, 25
	v_ashrrev_i32_e32 v103, 31, v102
	v_readlane_b32 s21, v254, 26
	s_mov_b64 s[38:39], -1
	s_waitcnt lgkmcnt(0)
	v_add_f32_e32 v26, v26, v27
	ds_bpermute_b32 v27, v105, v26
	v_lshl_add_u64 v[242:243], v[102:103], 2, s[20:21]
	v_add_u32_e32 v103, 0, v108
	s_waitcnt lgkmcnt(0)
	v_add_f32_e32 v26, v26, v27
	v_fmamk_f32 v26, v26, 0x3c800000, v205
	v_cmp_gt_f32_e32 vcc, s79, v26
	v_mul_f32_e32 v27, 0x4b800000, v26
	s_nop 0
	v_cndmask_b32_e32 v26, v26, v27, vcc
	v_rsq_f32_e32 v26, v26
	s_nop 0
	v_mul_f32_e32 v27, 0x45800000, v26
	v_cndmask_b32_e32 v46, v26, v27, vcc
	v_pk_mul_f32 v[26:27], v[6:7], v[46:47] op_sel_hi:[1,0]
	s_andn2_b64 vcc, exec, s[36:37]
	v_pk_mul_f32 v[58:59], v[26:27], v[34:35]
	ds_bpermute_b32 v60, v104, v58
	ds_bpermute_b32 v61, v104, v59
	ds_read_b128 v[66:69], v103 offset:20800
	ds_read_b128 v[70:73], v103 offset:23104
	ds_read_b128 v[74:77], v103 offset:25408
	ds_read_b128 v[78:81], v103 offset:27712
	ds_read_b128 v[82:85], v103 offset:30016
	ds_read_b128 v[86:89], v103 offset:32320
	ds_read_b128 v[110:113], v103 offset:34624
	v_pk_mul_f32 v[226:227], v[226:227], v[58:59]
	s_waitcnt lgkmcnt(7)
	v_pk_fma_f32 v[62:63], v[234:235], v[60:61], v[226:227] neg_lo:[1,0,0] neg_hi:[1,0,0]
	v_pk_fma_f32 v[234:235], v[234:235], v[60:61], v[226:227]
	v_pk_mul_f32 v[38:39], v[14:15], v[46:47] op_sel_hi:[1,0]
	v_cndmask_b32_e64 v234, v58, v234, s[44:45]
	v_pk_mul_f32 v[38:39], v[38:39], v[56:57]
	v_pk_mul_f32 v[56:57], v[8:9], v[46:47] op_sel_hi:[1,0]
	v_cndmask_b32_e64 v235, v59, v235, s[44:45]
	v_pk_mul_f32 v[54:55], v[56:57], v[54:55]
	ds_bpermute_b32 v56, v104, v54
	ds_bpermute_b32 v57, v104, v55
	v_cndmask_b32_e64 v235, v235, v63, s[42:43]
	v_cndmask_b32_e64 v234, v234, v62, s[42:43]
	v_pk_mul_f32 v[234:235], v[234:235], s[78:79] op_sel_hi:[1,0]
	v_pk_mul_f32 v[38:39], v[38:39], s[78:79] op_sel_hi:[1,0]
	s_waitcnt lgkmcnt(0)
; #define LAS __attribute__((address_space(3)))
; DI u32x4 pack8(const float* f) { u32x4 w; w.x = pk2(f[0], f[1]); w.y = pk2(f[2], f[3]); w.z = pk2(f[4], f[5]); w.w = pk2(f[6], f[7]); return w; }
;     DI float* fROPE() const { return (float*)(ws + WS_ROPE); }
; DI void attn_item(const Params& p, const Ctx& c, int l, int S, int tokbase, int qb, int kvh) {
;     ...
;         const float* rr = c.fROPE() + qpos * 16;
; #pragma unroll
;         for (int i = 0; i < 8; ++i) { const float other = __shfl_xor(f0[i], 16), cs = rr[i], sn = rr[8 + i];
;             if (lg == 0) f0[i] = f0[i] * cs - other * sn; else if (lg == 1) f0[i] = f0[i] * cs + other * sn; }
; #pragma unroll
;         for (int i = 0; i < 8; ++i) { f0[i] *= 0.18033688011112042f; f1[i] *= 0.18033688011112042f; }
;         const bf16x8 qf0 = __builtin_bit_cast(bf16x8, pack8(f0)), qf1 = __builtin_bit_cast(bf16x8, pack8(f1));
;         f32x4 s[17];
;         float mx = sink;
; #pragma unroll
;         for (int t = 0; t < 17; ++t) {
;             s[t] = (f32x4){0.f, 0.f, 0.f, 0.f};
;             const LAS bf16_t* kr = Ks + ((kt0 + t) * 16 + lr) * KP + lg * 8;
;             s[t] = __builtin_amdgcn_mfma_f32_16x16x32_bf16(*(const LAS bf16x8*)kr, qf0, s[t], 0, 0, 0);
;             s[t] = __builtin_amdgcn_mfma_f32_16x16x32_bf16(*(const LAS bf16x8*)(kr + 32), qf1, s[t], 0, 0, 0);
	v_pk_mul_f32 v[236:237], v[236:237], v[56:57]
	v_cvt_pk_bf16_f32 v94, v234, v235
	v_pk_fma_f32 v[56:57], v[228:229], v[54:55], v[236:237] neg_lo:[0,0,1] neg_hi:[0,0,1]
	v_pk_fma_f32 v[236:237], v[228:229], v[54:55], v[236:237]
	v_pk_mul_f32 v[40:41], v[16:17], v[46:47] op_sel_hi:[1,0]
	v_cndmask_b32_e64 v236, v54, v236, s[44:45]
	v_pk_mul_f32 v[40:41], v[40:41], v[52:53]
	v_pk_mul_f32 v[52:53], v[2:3], v[46:47] op_sel_hi:[1,0]
	v_cndmask_b32_e64 v237, v55, v237, s[44:45]
	v_pk_mul_f32 v[50:51], v[52:53], v[50:51]
	ds_bpermute_b32 v52, v104, v50
	ds_bpermute_b32 v53, v104, v51
	v_cndmask_b32_e64 v237, v237, v57, s[42:43]
	v_cndmask_b32_e64 v236, v236, v56, s[42:43]
	v_pk_mul_f32 v[236:237], v[236:237], s[78:79] op_sel_hi:[1,0]
	v_pk_mul_f32 v[40:41], v[40:41], s[78:79] op_sel_hi:[1,0]
	s_waitcnt lgkmcnt(0)
	v_pk_mul_f32 v[238:239], v[238:239], v[52:53]
	v_cvt_pk_bf16_f32 v95, v236, v237
	v_pk_fma_f32 v[52:53], v[50:51], v[230:231], v[238:239] neg_lo:[0,0,1] neg_hi:[0,0,1]
	v_pk_fma_f32 v[238:239], v[50:51], v[230:231], v[238:239]
	v_pk_mul_f32 v[30:31], v[10:11], v[46:47] op_sel_hi:[1,0]
	v_cndmask_b32_e64 v238, v50, v238, s[44:45]
	v_pk_mul_f32 v[30:31], v[30:31], v[48:49]
	v_pk_mul_f32 v[48:49], v[4:5], v[46:47] op_sel_hi:[1,0]
	v_cndmask_b32_e64 v239, v51, v239, s[44:45]
	v_pk_mul_f32 v[44:45], v[48:49], v[44:45]
	ds_bpermute_b32 v48, v104, v44
	ds_bpermute_b32 v49, v104, v45
	v_cndmask_b32_e64 v239, v239, v53, s[42:43]
	v_cndmask_b32_e64 v238, v238, v52, s[42:43]
	v_pk_mul_f32 v[238:239], v[238:239], s[78:79] op_sel_hi:[1,0]
	v_pk_mul_f32 v[30:31], v[30:31], s[78:79] op_sel_hi:[1,0]
	s_waitcnt lgkmcnt(0)
	v_pk_mul_f32 v[240:241], v[240:241], v[48:49]
	v_cvt_pk_bf16_f32 v96, v238, v239
	v_pk_fma_f32 v[48:49], v[44:45], v[232:233], v[240:241] neg_lo:[0,0,1] neg_hi:[0,0,1]
	v_pk_fma_f32 v[240:241], v[44:45], v[232:233], v[240:241]
	v_pk_mul_f32 v[32:33], v[12:13], v[46:47] op_sel_hi:[1,0]
	v_cndmask_b32_e64 v240, v44, v240, s[44:45]
	v_cndmask_b32_e64 v241, v45, v241, s[44:45]
	v_cndmask_b32_e64 v241, v241, v49, s[42:43]
	v_cndmask_b32_e64 v240, v240, v48, s[42:43]
	v_pk_mul_f32 v[240:241], v[240:241], s[78:79] op_sel_hi:[1,0]
	v_pk_mul_f32 v[32:33], v[32:33], v[42:43]
	v_cvt_pk_bf16_f32 v97, v240, v241
	s_cmp_eq_u32 s40, 48
	s_cbranch_scc1 .Lrope_pf_skip
	global_load_dwordx4 v[238:241], v[242:243], off offset:1072
	global_load_dwordx4 v[234:237], v[242:243], off offset:1056
	global_load_dwordx4 v[230:233], v[242:243], off offset:1040
	global_load_dwordx4 v[226:229], v[242:243], off offset:1024
.Lrope_pf_skip:
	ds_read_b128 v[26:29], v103
	v_pk_mul_f32 v[32:33], v[32:33], s[78:79] op_sel_hi:[1,0]
	v_cvt_pk_bf16_f32 v92, v30, v31
	v_cvt_pk_bf16_f32 v93, v32, v33
	ds_read_b128 v[30:33], v103 offset:64
	s_waitcnt lgkmcnt(1)
	v_mfma_f32_16x16x32_bf16 v[26:29], v[26:29], v[94:97], 0
	v_cvt_pk_bf16_f32 v90, v38, v39
	v_cvt_pk_bf16_f32 v91, v40, v41
	ds_read_b128 v[34:37], v103 offset:2368
	ds_read_b128 v[38:41], v103 offset:4672
	s_waitcnt lgkmcnt(2)
	v_mfma_f32_16x16x32_bf16 v[26:29], v[30:33], v[90:93], v[26:29]
	ds_read_b128 v[30:33], v103 offset:2304
	ds_read_b128 v[42:45], v103 offset:6976
	ds_read_b128 v[46:49], v103 offset:9280
	s_waitcnt lgkmcnt(2)
	v_mfma_f32_16x16x32_bf16 v[30:33], v[30:33], v[94:97], 0
	ds_read_b128 v[50:53], v103 offset:11584
	ds_read_b128 v[54:57], v103 offset:13888
	ds_read_b128 v[58:61], v103 offset:16192
	v_mfma_f32_16x16x32_bf16 v[30:33], v[34:37], v[90:93], v[30:33]
	ds_read_b128 v[34:37], v103 offset:4608
	ds_read_b128 v[62:65], v103 offset:18496
	s_waitcnt lgkmcnt(1)
	v_mfma_f32_16x16x32_bf16 v[34:37], v[34:37], v[94:97], 0
	v_mfma_f32_16x16x32_bf16 v[34:37], v[38:41], v[90:93], v[34:37]
	ds_read_b128 v[38:41], v103 offset:6912
	s_waitcnt lgkmcnt(0)
	v_mfma_f32_16x16x32_bf16 v[38:41], v[38:41], v[94:97], 0
	v_mfma_f32_16x16x32_bf16 v[38:41], v[42:45], v[90:93], v[38:41]
	ds_read_b128 v[42:45], v103 offset:9216
	s_waitcnt lgkmcnt(0)
	v_mfma_f32_16x16x32_bf16 v[42:45], v[42:45], v[94:97], 0
	v_mfma_f32_16x16x32_bf16 v[42:45], v[46:49], v[90:93], v[42:45]
	ds_read_b128 v[46:49], v103 offset:11520
	s_waitcnt lgkmcnt(0)
	v_mfma_f32_16x16x32_bf16 v[46:49], v[46:49], v[94:97], 0
	v_mfma_f32_16x16x32_bf16 v[46:49], v[50:53], v[90:93], v[46:49]
	ds_read_b128 v[50:53], v103 offset:13824
	s_waitcnt lgkmcnt(0)
	v_mfma_f32_16x16x32_bf16 v[50:53], v[50:53], v[94:97], 0
	v_mfma_f32_16x16x32_bf16 v[50:53], v[54:57], v[90:93], v[50:53]
	ds_read_b128 v[54:57], v103 offset:16128
	s_waitcnt lgkmcnt(0)
	v_mfma_f32_16x16x32_bf16 v[54:57], v[54:57], v[94:97], 0
	v_mfma_f32_16x16x32_bf16 v[54:57], v[58:61], v[90:93], v[54:57]
	ds_read_b128 v[58:61], v103 offset:18432
	s_waitcnt lgkmcnt(0)
	v_mfma_f32_16x16x32_bf16 v[58:61], v[58:61], v[94:97], 0
	v_mfma_f32_16x16x32_bf16 v[58:61], v[62:65], v[90:93], v[58:61]
	ds_read_b128 v[62:65], v103 offset:20736
	s_waitcnt lgkmcnt(0)
	v_mfma_f32_16x16x32_bf16 v[62:65], v[62:65], v[94:97], 0
	v_mfma_f32_16x16x32_bf16 v[62:65], v[66:69], v[90:93], v[62:65]
	ds_read_b128 v[66:69], v103 offset:23040
	s_waitcnt lgkmcnt(0)
	v_mfma_f32_16x16x32_bf16 v[66:69], v[66:69], v[94:97], 0
	v_mfma_f32_16x16x32_bf16 v[66:69], v[70:73], v[90:93], v[66:69]
	ds_read_b128 v[70:73], v103 offset:25344
	s_waitcnt lgkmcnt(0)
	v_mfma_f32_16x16x32_bf16 v[70:73], v[70:73], v[94:97], 0
	v_mfma_f32_16x16x32_bf16 v[70:73], v[74:77], v[90:93], v[70:73]
	ds_read_b128 v[74:77], v103 offset:27648
	s_waitcnt lgkmcnt(0)
	v_mfma_f32_16x16x32_bf16 v[74:77], v[74:77], v[94:97], 0
	v_mfma_f32_16x16x32_bf16 v[74:77], v[78:81], v[90:93], v[74:77]
	ds_read_b128 v[78:81], v103 offset:29952
	s_waitcnt lgkmcnt(0)
	v_mfma_f32_16x16x32_bf16 v[78:81], v[78:81], v[94:97], 0
	v_mfma_f32_16x16x32_bf16 v[78:81], v[82:85], v[90:93], v[78:81]
	ds_read_b128 v[82:85], v103 offset:32256
	s_waitcnt lgkmcnt(0)
	v_mfma_f32_16x16x32_bf16 v[82:85], v[82:85], v[94:97], 0
	v_mfma_f32_16x16x32_bf16 v[82:85], v[86:89], v[90:93], v[82:85]
	ds_read_b128 v[86:89], v103 offset:34560
	s_waitcnt lgkmcnt(0)
	v_mfma_f32_16x16x32_bf16 v[86:89], v[86:89], v[94:97], 0
	v_mfma_f32_16x16x32_bf16 v[86:89], v[110:113], v[90:93], v[86:89]
	ds_read_b128 v[110:113], v103 offset:36864
	s_waitcnt lgkmcnt(0)
	v_mfma_f32_16x16x32_bf16 v[94:97], v[110:113], v[94:97], 0
	ds_read_b128 v[110:113], v103 offset:36928
	s_waitcnt lgkmcnt(0)
	v_mfma_f32_16x16x32_bf16 v[90:93], v[110:113], v[90:93], v[94:97]
	s_cbranch_vccnz .LBB0_321
; DI void attn_item(const Params& p, const Ctx& c, int l, int S, int tokbase, int qb, int kvh) {
;     ...
; #pragma unroll
;             for (int t = 0; t < 17; ++t)
; #pragma unroll
;                 for (int r = 0; r < 4; ++r) { const int kpos = kstart + (kt0 + t) * 16 + lg * 4 + r;
;                     bool valid = (kpos >= 0) && (kpos < S);
;                     if (t == 0) valid = valid && (lg * 4 + r >= lr);
;                     if (t == 16) valid = valid && (lg * 4 + r <= lr);
;                     const float v = valid ? s[t][r] : -INFINITY; s[t][r] = v; mx = fmaxf(mx, v); }
	s_add_i32 s2, s41, s40
	s_add_i32 s20, s2, 0xffffff80
	v_add_u32_e32 v144, s40, v109
	v_add_u32_e32 v94, 0xffffff80, v144
	s_cmp_gt_i32 s20, -1
	s_cselect_b64 s[20:21], -1, 0
	v_cmp_gt_i32_e32 vcc, s30, v94
	s_and_b64 s[24:25], s[20:21], vcc
	s_and_b64 vcc, s[24:25], s[46:47]
	v_add_u32_e32 v94, 0xffffff81, v144
	v_cndmask_b32_e32 v26, v208, v26, vcc
	v_cmp_gt_i32_e32 vcc, s30, v94
	s_and_b64 s[24:25], s[20:21], vcc
	s_and_b64 vcc, s[24:25], s[48:49]
	v_add_u32_e32 v95, 0xffffff82, v144
	v_cndmask_b32_e32 v27, v208, v27, vcc
	v_cmp_gt_i32_e32 vcc, s30, v95
	s_and_b64 s[24:25], s[20:21], vcc
	s_and_b64 vcc, s[24:25], s[50:51]
	v_add_u32_e32 v95, 0xffffff83, v144
	v_cndmask_b32_e32 v28, v208, v28, vcc
	v_cmp_gt_i32_e32 vcc, s30, v95
	s_and_b64 s[20:21], s[20:21], vcc
	s_and_b64 vcc, s[20:21], s[52:53]
	s_add_i32 s20, s2, 0xffffff90
	v_add_u32_e32 v95, 0xffffff90, v144
	s_cmp_gt_i32 s20, -1
	v_cndmask_b32_e32 v29, v208, v29, vcc
	s_cselect_b64 s[20:21], -1, 0
	v_cmp_gt_i32_e32 vcc, s30, v95
	s_and_b64 vcc, s[20:21], vcc
	v_add_u32_e32 v95, 0xffffff91, v144
	v_cndmask_b32_e32 v30, v208, v30, vcc
	v_cmp_gt_i32_e32 vcc, s30, v95
	s_and_b64 vcc, s[20:21], vcc
	v_add_u32_e32 v95, 0xffffff92, v144
	v_cndmask_b32_e32 v31, v208, v31, vcc
	v_cmp_gt_i32_e32 vcc, s30, v95
	s_and_b64 vcc, s[20:21], vcc
	v_add_u32_e32 v95, 0xffffff93, v144
	v_cndmask_b32_e32 v32, v208, v32, vcc
	v_cmp_gt_i32_e32 vcc, s30, v95
	s_and_b64 vcc, s[20:21], vcc
	s_add_i32 s20, s2, 0xffffffa0
	v_add_u32_e32 v95, 0xffffffa0, v144
	s_cmp_gt_i32 s20, -1
	v_cndmask_b32_e32 v33, v208, v33, vcc
	s_cselect_b64 s[20:21], -1, 0
	v_cmp_gt_i32_e32 vcc, s30, v95
	s_and_b64 vcc, s[20:21], vcc
	v_add_u32_e32 v95, 0xffffffa1, v144
	v_cndmask_b32_e32 v34, v208, v34, vcc
	v_cmp_gt_i32_e32 vcc, s30, v95
	s_and_b64 vcc, s[20:21], vcc
	v_add_u32_e32 v95, 0xffffffa2, v144
	v_cndmask_b32_e32 v35, v208, v35, vcc
	v_cmp_gt_i32_e32 vcc, s30, v95
	s_and_b64 vcc, s[20:21], vcc
	v_add_u32_e32 v95, 0xffffffa3, v144
	v_cndmask_b32_e32 v36, v208, v36, vcc
	v_cmp_gt_i32_e32 vcc, s30, v95
	s_and_b64 vcc, s[20:21], vcc
	s_add_i32 s20, s2, 0xffffffb0
	v_add_u32_e32 v95, 0xffffffb0, v144
	s_cmp_gt_i32 s20, -1
	v_cndmask_b32_e32 v37, v208, v37, vcc
	s_cselect_b64 s[20:21], -1, 0
	v_cmp_gt_i32_e32 vcc, s30, v95
	s_and_b64 vcc, s[20:21], vcc
	v_add_u32_e32 v95, 0xffffffb1, v144
	v_cndmask_b32_e32 v38, v208, v38, vcc
	v_cmp_gt_i32_e32 vcc, s30, v95
	s_and_b64 vcc, s[20:21], vcc
	v_add_u32_e32 v95, 0xffffffb2, v144
	v_cndmask_b32_e32 v39, v208, v39, vcc
	v_cmp_gt_i32_e32 vcc, s30, v95
	s_and_b64 vcc, s[20:21], vcc
	v_add_u32_e32 v95, 0xffffffb3, v144
	v_cndmask_b32_e32 v40, v208, v40, vcc
	v_cmp_gt_i32_e32 vcc, s30, v95
	s_and_b64 vcc, s[20:21], vcc
	s_sub_i32 s20, s2, 64
	v_subrev_u32_e32 v95, 64, v144
	s_cmp_gt_i32 s20, -1
	v_cndmask_b32_e32 v41, v208, v41, vcc
	s_cselect_b64 s[20:21], -1, 0
	v_cmp_gt_i32_e32 vcc, s30, v95
	s_and_b64 vcc, s[20:21], vcc
	v_subrev_u32_e32 v95, 63, v144
	v_cndmask_b32_e32 v42, v208, v42, vcc
	v_cmp_gt_i32_e32 vcc, s30, v95
	s_and_b64 vcc, s[20:21], vcc
	v_subrev_u32_e32 v95, 62, v144
	v_cndmask_b32_e32 v43, v208, v43, vcc
	v_cmp_gt_i32_e32 vcc, s30, v95
	s_and_b64 vcc, s[20:21], vcc
	v_subrev_u32_e32 v95, 61, v144
	v_cndmask_b32_e32 v44, v208, v44, vcc
	v_cmp_gt_i32_e32 vcc, s30, v95
	s_and_b64 vcc, s[20:21], vcc
	s_sub_i32 s20, s2, 48
	v_subrev_u32_e32 v95, 48, v144
	s_cmp_gt_i32 s20, -1
	v_cndmask_b32_e32 v45, v208, v45, vcc
	s_cselect_b64 s[20:21], -1, 0
	v_cmp_gt_i32_e32 vcc, s30, v95
	s_and_b64 vcc, s[20:21], vcc
	v_subrev_u32_e32 v95, 47, v144
	v_cndmask_b32_e32 v46, v208, v46, vcc
	v_cmp_gt_i32_e32 vcc, s30, v95
	s_and_b64 vcc, s[20:21], vcc
	v_subrev_u32_e32 v95, 46, v144
	v_cndmask_b32_e32 v47, v208, v47, vcc
	v_cmp_gt_i32_e32 vcc, s30, v95
	s_and_b64 vcc, s[20:21], vcc
	v_subrev_u32_e32 v95, 45, v144
	v_cndmask_b32_e32 v48, v208, v48, vcc
	v_cmp_gt_i32_e32 vcc, s30, v95
	s_and_b64 vcc, s[20:21], vcc
	s_sub_i32 s20, s2, 32
	v_subrev_u32_e32 v95, 32, v144
	s_cmp_gt_i32 s20, -1
	v_cndmask_b32_e32 v49, v208, v49, vcc
	s_cselect_b64 s[20:21], -1, 0
	v_cmp_gt_i32_e32 vcc, s30, v95
	s_and_b64 vcc, s[20:21], vcc
	v_subrev_u32_e32 v95, 31, v144
	v_cndmask_b32_e32 v50, v208, v50, vcc
	v_cmp_gt_i32_e32 vcc, s30, v95
	s_and_b64 vcc, s[20:21], vcc
	v_subrev_u32_e32 v95, 30, v144
	v_cndmask_b32_e32 v51, v208, v51, vcc
	v_cmp_gt_i32_e32 vcc, s30, v95
	s_and_b64 vcc, s[20:21], vcc
	v_subrev_u32_e32 v95, 29, v144
	v_cndmask_b32_e32 v52, v208, v52, vcc
	v_cmp_gt_i32_e32 vcc, s30, v95
	s_and_b64 vcc, s[20:21], vcc
	s_add_i32 s20, s2, -16
	v_add_u32_e32 v95, -16, v144
	s_cmp_gt_i32 s20, -1
	v_cndmask_b32_e32 v53, v208, v53, vcc
	s_cselect_b64 s[20:21], -1, 0
	v_cmp_gt_i32_e32 vcc, s30, v95
	s_and_b64 vcc, s[20:21], vcc
	v_add_u32_e32 v95, -15, v144
	v_cndmask_b32_e32 v54, v208, v54, vcc
	v_cmp_gt_i32_e32 vcc, s30, v95
	s_and_b64 vcc, s[20:21], vcc
	v_add_u32_e32 v95, -14, v144
	v_cndmask_b32_e32 v55, v208, v55, vcc
	v_cmp_gt_i32_e32 vcc, s30, v95
	s_and_b64 vcc, s[20:21], vcc
	v_add_u32_e32 v95, -13, v144
	v_cndmask_b32_e32 v56, v208, v56, vcc
	v_cmp_gt_i32_e32 vcc, s30, v95
	s_and_b64 vcc, s[20:21], vcc
	s_cmp_gt_i32 s2, -1
	v_cndmask_b32_e32 v57, v208, v57, vcc
	s_cselect_b64 s[20:21], -1, 0
	v_cmp_gt_i32_e32 vcc, s30, v144
	s_and_b64 vcc, s[20:21], vcc
	v_add_u32_e32 v95, 1, v144
	v_cndmask_b32_e32 v58, v208, v58, vcc
	v_cmp_gt_i32_e32 vcc, s30, v95
	s_and_b64 vcc, s[20:21], vcc
	v_add_u32_e32 v95, 2, v144
	v_cndmask_b32_e32 v59, v208, v59, vcc
	v_cmp_gt_i32_e32 vcc, s30, v95
	s_and_b64 vcc, s[20:21], vcc
	v_add_u32_e32 v95, 3, v144
	v_cndmask_b32_e32 v60, v208, v60, vcc
; DI void attn_item(const Params& p, const Ctx& c, int l, int S, int tokbase, int qb, int kvh) {
;     ...
; #pragma unroll
;             for (int t = 0; t < 17; ++t)
; #pragma unroll
;                 for (int r = 0; r < 4; ++r) { const int kpos = kstart + (kt0 + t) * 16 + lg * 4 + r;
;                     bool valid = (kpos >= 0) && (kpos < S);
;                     if (t == 0) valid = valid && (lg * 4 + r >= lr);
;                     if (t == 16) valid = valid && (lg * 4 + r <= lr);
;                     const float v = valid ? s[t][r] : -INFINITY; s[t][r] = v; mx = fmaxf(mx, v); }
;         }
	v_cmp_gt_i32_e32 vcc, s30, v95
	s_and_b64 vcc, s[20:21], vcc
	s_add_i32 s20, s2, 16
	v_add_u32_e32 v95, 16, v144
	s_cmp_gt_i32 s20, -1
	v_cndmask_b32_e32 v61, v208, v61, vcc
	s_cselect_b64 s[20:21], -1, 0
	v_cmp_gt_i32_e32 vcc, s30, v95
	s_and_b64 vcc, s[20:21], vcc
	v_add_u32_e32 v95, 17, v144
	v_cndmask_b32_e32 v62, v208, v62, vcc
	v_cmp_gt_i32_e32 vcc, s30, v95
	s_and_b64 vcc, s[20:21], vcc
	v_add_u32_e32 v95, 18, v144
	v_cndmask_b32_e32 v63, v208, v63, vcc
	v_cmp_gt_i32_e32 vcc, s30, v95
	s_and_b64 vcc, s[20:21], vcc
	v_add_u32_e32 v95, 19, v144
	v_cndmask_b32_e32 v64, v208, v64, vcc
	v_cmp_gt_i32_e32 vcc, s30, v95
	s_and_b64 vcc, s[20:21], vcc
	s_add_i32 s20, s2, 32
	v_add_u32_e32 v95, 32, v144
	s_cmp_gt_i32 s20, -1
	v_cndmask_b32_e32 v65, v208, v65, vcc
	s_cselect_b64 s[20:21], -1, 0
	v_cmp_gt_i32_e32 vcc, s30, v95
	s_and_b64 vcc, s[20:21], vcc
	v_add_u32_e32 v95, 33, v144
	v_cndmask_b32_e32 v66, v208, v66, vcc
	v_cmp_gt_i32_e32 vcc, s30, v95
	s_and_b64 vcc, s[20:21], vcc
	v_add_u32_e32 v95, 34, v144
	v_cndmask_b32_e32 v67, v208, v67, vcc
	v_cmp_gt_i32_e32 vcc, s30, v95
	s_and_b64 vcc, s[20:21], vcc
	v_add_u32_e32 v95, 35, v144
	v_cndmask_b32_e32 v68, v208, v68, vcc
	v_cmp_gt_i32_e32 vcc, s30, v95
	s_and_b64 vcc, s[20:21], vcc
	s_add_i32 s20, s2, 48
	v_add_u32_e32 v95, 48, v144
	s_cmp_gt_i32 s20, -1
	v_max3_f32 v94, v106, v26, v27
	v_cndmask_b32_e32 v69, v208, v69, vcc
	s_cselect_b64 s[20:21], -1, 0
	v_cmp_gt_i32_e32 vcc, s30, v95
	v_max3_f32 v94, v94, v28, v29
	s_and_b64 vcc, s[20:21], vcc
	v_add_u32_e32 v95, 49, v144
	v_max3_f32 v94, v94, v30, v31
	v_cndmask_b32_e32 v70, v208, v70, vcc
	v_cmp_gt_i32_e32 vcc, s30, v95
	v_max3_f32 v94, v94, v32, v33
	s_and_b64 vcc, s[20:21], vcc
	v_add_u32_e32 v95, 50, v144
	v_max3_f32 v94, v94, v34, v35
	v_cndmask_b32_e32 v71, v208, v71, vcc
	v_cmp_gt_i32_e32 vcc, s30, v95
	v_max3_f32 v94, v94, v36, v37
	s_and_b64 vcc, s[20:21], vcc
	v_add_u32_e32 v95, 51, v144
	v_max3_f32 v94, v94, v38, v39
	v_cndmask_b32_e32 v72, v208, v72, vcc
	v_cmp_gt_i32_e32 vcc, s30, v95
	v_max3_f32 v94, v94, v40, v41
	s_and_b64 vcc, s[20:21], vcc
	s_add_i32 s20, s2, 64
	v_max3_f32 v94, v94, v42, v43
	v_add_u32_e32 v95, 64, v144
	s_cmp_gt_i32 s20, -1
	v_max3_f32 v94, v94, v44, v45
	v_cndmask_b32_e32 v73, v208, v73, vcc
	s_cselect_b64 s[20:21], -1, 0
	v_cmp_gt_i32_e32 vcc, s30, v95
	v_max3_f32 v94, v94, v46, v47
	s_and_b64 vcc, s[20:21], vcc
	v_add_u32_e32 v95, 0x41, v144
	v_max3_f32 v94, v94, v48, v49
	v_cndmask_b32_e32 v74, v208, v74, vcc
	v_cmp_gt_i32_e32 vcc, s30, v95
	v_max3_f32 v94, v94, v50, v51
	s_and_b64 vcc, s[20:21], vcc
	v_add_u32_e32 v95, 0x42, v144
	v_max3_f32 v94, v94, v52, v53
	v_cndmask_b32_e32 v75, v208, v75, vcc
	v_cmp_gt_i32_e32 vcc, s30, v95
	v_max3_f32 v94, v94, v54, v55
	s_and_b64 vcc, s[20:21], vcc
	v_add_u32_e32 v95, 0x43, v144
	v_max3_f32 v94, v94, v56, v57
	v_cndmask_b32_e32 v76, v208, v76, vcc
	v_cmp_gt_i32_e32 vcc, s30, v95
	v_max3_f32 v94, v94, v58, v59
	s_and_b64 vcc, s[20:21], vcc
	s_add_i32 s20, s2, 0x50
	v_max3_f32 v94, v94, v60, v61
	v_add_u32_e32 v95, 0x50, v144
	s_cmp_gt_i32 s20, -1
	v_max3_f32 v94, v94, v62, v63
	v_cndmask_b32_e32 v77, v208, v77, vcc
	s_cselect_b64 s[20:21], -1, 0
	v_cmp_gt_i32_e32 vcc, s30, v95
	v_max3_f32 v94, v94, v64, v65
	s_and_b64 vcc, s[20:21], vcc
	v_add_u32_e32 v95, 0x51, v144
	v_max3_f32 v94, v94, v66, v67
	v_cndmask_b32_e32 v78, v208, v78, vcc
	v_cmp_gt_i32_e32 vcc, s30, v95
	v_max3_f32 v94, v94, v68, v69
	s_and_b64 vcc, s[20:21], vcc
	v_add_u32_e32 v95, 0x52, v144
	v_max3_f32 v94, v94, v70, v71
	v_cndmask_b32_e32 v79, v208, v79, vcc
	v_cmp_gt_i32_e32 vcc, s30, v95
	v_max3_f32 v94, v94, v72, v73
	s_and_b64 vcc, s[20:21], vcc
	v_add_u32_e32 v95, 0x53, v144
	v_max3_f32 v94, v94, v74, v75
	v_cndmask_b32_e32 v80, v208, v80, vcc
	v_cmp_gt_i32_e32 vcc, s30, v95
	v_max3_f32 v94, v94, v76, v77
	s_and_b64 vcc, s[20:21], vcc
	v_max3_f32 v94, v94, v78, v79
	v_cndmask_b32_e32 v81, v208, v81, vcc
	s_add_i32 s20, s2, 0x60
	v_max3_f32 v95, v94, v80, v81
	v_add_u32_e32 v94, 0x60, v144
	s_cmp_gt_i32 s20, -1
	s_cselect_b64 s[20:21], -1, 0
	v_cmp_gt_i32_e32 vcc, s30, v94
	s_and_b64 vcc, s[20:21], vcc
	v_add_u32_e32 v110, 0x61, v144
	v_cndmask_b32_e32 v82, v208, v82, vcc
	v_cmp_gt_i32_e32 vcc, s30, v110
	s_and_b64 vcc, s[20:21], vcc
	v_add_u32_e32 v110, 0x62, v144
	v_cndmask_b32_e32 v83, v208, v83, vcc
	v_cmp_gt_i32_e32 vcc, s30, v110
	s_and_b64 vcc, s[20:21], vcc
	v_add_u32_e32 v110, 0x63, v144
	v_cndmask_b32_e32 v84, v208, v84, vcc
	v_cmp_gt_i32_e32 vcc, s30, v110
	s_and_b64 vcc, s[20:21], vcc
	v_max3_f32 v95, v95, v82, v83
	v_cndmask_b32_e32 v85, v208, v85, vcc
	s_add_i32 s20, s2, 0x70
	v_max3_f32 v110, v95, v84, v85
	v_add_u32_e32 v95, 0x70, v144
	s_cmp_gt_i32 s20, -1
	s_cselect_b64 s[20:21], -1, 0
	v_cmp_gt_i32_e32 vcc, s30, v95
	s_and_b64 vcc, s[20:21], vcc
	v_add_u32_e32 v111, 0x71, v144
	v_cndmask_b32_e32 v86, v208, v86, vcc
	v_cmp_gt_i32_e32 vcc, s30, v111
	s_and_b64 vcc, s[20:21], vcc
	v_add_u32_e32 v111, 0x72, v144
	v_cndmask_b32_e32 v87, v208, v87, vcc
	v_cmp_gt_i32_e32 vcc, s30, v111
	s_and_b64 vcc, s[20:21], vcc
	v_add_u32_e32 v111, 0x73, v144
	v_cndmask_b32_e32 v88, v208, v88, vcc
	v_cmp_gt_i32_e32 vcc, s30, v111
	s_and_b64 vcc, s[20:21], vcc
	v_max3_f32 v110, v110, v86, v87
	v_cndmask_b32_e32 v89, v208, v89, vcc
	s_addk_i32 s2, 0x80
	v_max3_f32 v121, v110, v88, v89
	v_add_u32_e32 v110, 0x80, v144
	s_cmp_gt_i32 s2, -1
	s_cselect_b64 s[20:21], -1, 0
	v_cmp_gt_i32_e32 vcc, s30, v110
	s_and_b64 s[24:25], s[20:21], vcc
	s_and_b64 vcc, s[24:25], s[54:55]
	v_add_u32_e32 v111, 0x81, v144
	v_cndmask_b32_e32 v90, v208, v90, vcc
	v_cmp_gt_i32_e32 vcc, s30, v111
	s_and_b64 s[24:25], s[20:21], vcc
	s_and_b64 vcc, s[24:25], s[56:57]
	v_cndmask_b32_e32 v91, v208, v91, vcc
	v_max3_f32 v174, v121, v90, v91
	v_add_u32_e32 v121, 0x82, v144
	v_cmp_gt_i32_e32 vcc, s30, v121
	s_and_b64 s[24:25], s[20:21], vcc
	s_and_b64 vcc, s[24:25], s[58:59]
	v_add_u32_e32 v144, 0x83, v144
	v_cndmask_b32_e32 v92, v208, v92, vcc
	v_cmp_gt_i32_e32 vcc, s30, v144
	s_and_b64 s[20:21], s[20:21], vcc
	s_and_b64 vcc, s[20:21], s[60:61]
	v_cndmask_b32_e32 v93, v208, v93, vcc
	v_max3_f32 v188, v174, v92, v93
	s_mov_b64 s[38:39], 0
